# back-edge rotation (7.11) on the attention fast loops: slot rotation / counter / exit test SALU moved in front of the step barriers, loop-back barrier is the loop head, exit path has its own barrier c
# speedup vs baseline: 1.0034x; 1.0034x over previous
;   #define WB(a,b) do{ if constexpr(DV2){WAIT_BAR(b);} else {WAIT_BAR(a);} }while(0)
;   #define RESC() do{ if(resc){ asm volatile("s_waitcnt lgkmcnt(0)":::"memory"); \
;       _Pragma("unroll") for(int d_=0;d_<ND;++d_) _Pragma("unroll") for(int r=0;r<16;++r)o[d_][r]*=wsf[crow(r,hi)]; } }while(0)
;   #define ROT() do{sl_prev=sl_cur;sl_cur=sl_next;sl_next=(sl_next==(NSLOT-1)*SLOTB)?0:sl_next+SLOTB;}while(0)
;     ...
;   for(;t+5<NT;t+=2){
;     STEP(pB0,pB1,pA0,pA1,t,true,true,true);     WB(2,3); RESC(); ROT();
;     STEP(pA0,pA1,pB0,pB1,t+1,true,true,true);   WB(2,3); RESC(); ROT();
;   }
.LBB0_266:
	s_add_i32 s16, s47, 0x2000
	s_cmpk_lg_i32 s47, 0x4000
	s_cselect_b32 s46, s16, 0
	s_add_i32 s16, s20, 2
	s_add_u32 s14, s14, 0x4000
	s_addc_u32 s15, s15, 0
	s_cmp_ge_u32 s16, s39
	s_cbranch_scc1 .LBB0_281
	s_mov_b32 s20, s16
	s_mov_b32 s22, s13
	s_mov_b32 s21, s47
	s_mov_b32 s13, s46
	s_branch .LBB0_260
.Lfsk2_head:
	s_waitcnt vmcnt(3) lgkmcnt(0)
	s_barrier
.Lfsk2_260:
	v_add_u32_e32 v0, s22, v251
	ds_read_b64_tr_b16 v[198:199], v0 offset:24576
	ds_read_b64_tr_b16 v[200:201], v0 offset:25088
	s_waitcnt lgkmcnt(9)
	v_mfma_f32_32x32x16_bf16 v[130:145], v[194:197], v[162:165], v[208:223]
	v_add_f32_e32 v230, v98, v99
	v_cvt_pk_bf16_f32 v150, v98, v99
	v_add_f32_e32 v231, v100, v101
	v_cvt_pk_bf16_f32 v151, v100, v101
	v_add_f32_e32 v230, v102, v230
	v_add_f32_e32 v231, v103, v231
	ds_read_b64_tr_b16 v[194:195], v0 offset:28672
	ds_read_b64_tr_b16 v[196:197], v0 offset:29184
	s_waitcnt lgkmcnt(10)
	v_mfma_f32_32x32x16_bf16 v[114:129], v[186:189], v[162:165], v[208:223]
	v_add_f32_e32 v230, v104, v230
	v_cvt_pk_bf16_f32 v152, v102, v103
	v_add_f32_e32 v231, v105, v231
	v_cvt_pk_bf16_f32 v153, v104, v105
	v_add_f32_e32 v230, v106, v230
	v_add_f32_e32 v231, v107, v231
	ds_read_b64_tr_b16 v[102:103], v0 offset:25600
	ds_read_b64_tr_b16 v[104:105], v0 offset:26112
	s_waitcnt lgkmcnt(11)
	v_mfma_f32_32x32x16_bf16 v[130:145], v[190:193], v[158:161], v[130:145]
	v_add_f32_e32 v230, v108, v230
	v_cvt_pk_bf16_f32 v10, v106, v107
	v_add_f32_e32 v231, v109, v231
	v_cvt_pk_bf16_f32 v11, v108, v109
	v_add_f32_e32 v230, v110, v230
	v_add_f32_e32 v231, v111, v231
	ds_read_b64_tr_b16 v[98:99], v0 offset:29696
	ds_read_b64_tr_b16 v[100:101], v0 offset:30208
	s_waitcnt lgkmcnt(12)
	v_mfma_f32_32x32x16_bf16 v[114:129], v[182:185], v[158:161], v[114:129]
	v_add_f32_e32 v230, v112, v230
	v_cvt_pk_bf16_f32 v12, v110, v111
	v_add_f32_e32 v231, v113, v231
	v_cvt_pk_bf16_f32 v13, v112, v113
	v_add_f32_e32 v230, v82, v230
	v_add_f32_e32 v231, v83, v231
	ds_read_b64_tr_b16 v[110:111], v0 offset:26624
	ds_read_b64_tr_b16 v[112:113], v0 offset:27136
	s_waitcnt lgkmcnt(13)
	v_mfma_f32_32x32x16_bf16 v[130:145], v[178:181], v[154:157], v[130:145]
	v_add_f32_e32 v230, v84, v230
	v_cvt_pk_bf16_f32 v6, v82, v83
	v_add_f32_e32 v231, v85, v231
	v_cvt_pk_bf16_f32 v7, v84, v85
	v_add_f32_e32 v230, v86, v230
	v_add_f32_e32 v231, v87, v231
	ds_read_b64_tr_b16 v[106:107], v0 offset:30720
	ds_read_b64_tr_b16 v[108:109], v0 offset:31232
	s_waitcnt lgkmcnt(14)
	v_mfma_f32_32x32x16_bf16 v[114:129], v[174:177], v[154:157], v[114:129]
	v_add_f32_e32 v230, v88, v230
	v_cvt_pk_bf16_f32 v8, v86, v87
	v_add_f32_e32 v231, v89, v231
	v_cvt_pk_bf16_f32 v9, v88, v89
	v_add_f32_e32 v230, v90, v230
	v_add_f32_e32 v231, v91, v231
	ds_read_b64_tr_b16 v[86:87], v0 offset:27648
	ds_read_b64_tr_b16 v[88:89], v0 offset:28160
	s_waitcnt lgkmcnt(14)
	v_mfma_f32_32x32x16_bf16 v[130:145], v[170:173], v[146:149], v[130:145]
	v_add_f32_e32 v230, v92, v230
	v_cvt_pk_bf16_f32 v2, v90, v91
	v_add_f32_e32 v231, v93, v231
	v_cvt_pk_bf16_f32 v3, v92, v93
	v_add_f32_e32 v230, v94, v230
	v_add_f32_e32 v231, v95, v231
	ds_read_b64_tr_b16 v[82:83], v0 offset:31744
	ds_read_b64_tr_b16 v[84:85], v0 offset:32256
	v_mfma_f32_32x32x16_bf16 v[114:129], v[166:169], v[146:149], v[114:129]
	v_add_f32_e32 v230, v96, v230
	v_cvt_pk_bf16_f32 v4, v94, v95
	v_add_f32_e32 v231, v97, v231
	v_cvt_pk_bf16_f32 v5, v96, v97
	s_add_u32 s54, s48, s14
	s_addc_u32 s55, s49, s15
	s_add_u32 s56, s54, 0x8000
	s_addc_u32 s57, s55, 0
	s_add_i32 s16, s21, s43
	s_mov_b32 m0, s16
	s_nop 0
	global_load_lds_dwordx4 v202, s[56:57]
	s_add_u32 s56, s50, s14
	s_addc_u32 s57, s51, s15
	s_add_u32 s56, s56, 0x4000
	s_addc_u32 s57, s57, 0
	s_add_i32 s16, s13, s44
	s_mov_b32 m0, s16
	s_nop 0
	global_load_lds_dwordx4 v203, s[56:57]
	s_add_u32 s58, s52, s14
	s_addc_u32 s59, s53, s15
	s_add_u32 s58, s58, 0x4000
	s_addc_u32 s59, s59, 0
	s_add_i32 s16, s13, s45
	s_mov_b32 m0, s16
	s_nop 0
	global_load_lds_dwordx4 v203, s[58:59]
	v_add_f32_e32 v230, v230, v231
	v_add_f32_e32 v206, v232, v230
.Lfsk2_261:
	v_add_u32_e32 v0, s22, v249
	v_add_u32_e32 v166, 0xe800, v0
	s_waitcnt lgkmcnt(14)
	v_mfma_f32_32x32x16_bf16 v[66:81], v[150:153], v[198:201], v[66:81]
	v_exp_f32_e32 v130, v130
	v_exp_f32_e32 v131, v131
	ds_read_b64_tr_b16 v[90:91], v0 offset:59392
	ds_read_b64_tr_b16 v[92:93], v0 offset:59904
	s_waitcnt lgkmcnt(14)
	v_mfma_f32_32x32x16_bf16 v[50:65], v[150:153], v[194:197], v[50:65]
	v_exp_f32_e32 v132, v132
	v_exp_f32_e32 v133, v133
	ds_read_b64_tr_b16 v[94:95], v0 offset:63488
	ds_read_b64_tr_b16 v[96:97], v0 offset:64000
	s_waitcnt lgkmcnt(14)
	v_mfma_f32_32x32x16_bf16 v[66:81], v[10:13], v[102:105], v[66:81]
	v_exp_f32_e32 v134, v134
	v_exp_f32_e32 v135, v135
	ds_read_b64_tr_b16 v[102:103], v0 offset:60416
	ds_read_b64_tr_b16 v[104:105], v0 offset:60928
	s_waitcnt lgkmcnt(14)
	v_mfma_f32_32x32x16_bf16 v[50:65], v[10:13], v[98:101], v[50:65]
	v_exp_f32_e32 v136, v136
	v_exp_f32_e32 v137, v137
	ds_read_b64_tr_b16 v[98:99], v0 offset:64512
	ds_read_b64_tr_b16 v[100:101], v0 offset:65024
	s_waitcnt lgkmcnt(14)
	v_mfma_f32_32x32x16_bf16 v[66:81], v[6:9], v[110:113], v[66:81]
	v_exp_f32_e32 v138, v138
	v_exp_f32_e32 v139, v139
	ds_read_b64_tr_b16 v[110:111], v0 offset:61440
	ds_read_b64_tr_b16 v[112:113], v0 offset:61952
	s_waitcnt lgkmcnt(14)
	v_mfma_f32_32x32x16_bf16 v[50:65], v[6:9], v[106:109], v[50:65]
	v_exp_f32_e32 v140, v140
	v_exp_f32_e32 v141, v141
	ds_read_b64_tr_b16 v[106:107], v166 offset:6144
	ds_read_b64_tr_b16 v[108:109], v166 offset:6656
	s_waitcnt lgkmcnt(14)
	v_mfma_f32_32x32x16_bf16 v[66:81], v[2:5], v[86:89], v[66:81]
	v_exp_f32_e32 v142, v142
	v_exp_f32_e32 v143, v143
	ds_read_b64_tr_b16 v[190:191], v0 offset:62464
	ds_read_b64_tr_b16 v[192:193], v0 offset:62976
	s_waitcnt lgkmcnt(14)
	v_mfma_f32_32x32x16_bf16 v[50:65], v[2:5], v[82:85], v[50:65]
	v_exp_f32_e32 v144, v144
	v_exp_f32_e32 v145, v145
	ds_read_b64_tr_b16 v[194:195], v166 offset:7168
	ds_read_b64_tr_b16 v[196:197], v166 offset:7680
	s_waitcnt lgkmcnt(14)
	v_mfma_f32_32x32x16_bf16 v[34:49], v[150:153], v[90:93], v[34:49]
	v_exp_f32_e32 v114, v114
	v_exp_f32_e32 v115, v115
	s_waitcnt lgkmcnt(12)
	v_mfma_f32_32x32x16_bf16 v[18:33], v[150:153], v[94:97], v[18:33]
	v_exp_f32_e32 v116, v116
	v_exp_f32_e32 v117, v117
	v_add_u32_e32 v0, s13, v250
	ds_read_b128 v[86:89], v0
	ds_read_b128 v[82:85], v0 offset:512
	s_waitcnt lgkmcnt(12)
	v_mfma_f32_32x32x16_bf16 v[34:49], v[10:13], v[102:105], v[34:49]
	v_exp_f32_e32 v118, v118
	v_exp_f32_e32 v119, v119
	ds_read_b128 v[186:189], v0 offset:2048
	ds_read_b128 v[182:185], v0 offset:2560
	s_waitcnt lgkmcnt(12)
	v_mfma_f32_32x32x16_bf16 v[18:33], v[10:13], v[98:101], v[18:33]
	v_exp_f32_e32 v120, v120
	v_exp_f32_e32 v121, v121
	ds_read_b128 v[178:181], v0 offset:4096
	ds_read_b128 v[174:177], v0 offset:4608
	s_waitcnt lgkmcnt(12)
	v_mfma_f32_32x32x16_bf16 v[34:49], v[6:9], v[110:113], v[34:49]
	v_exp_f32_e32 v122, v122
	v_exp_f32_e32 v123, v123
	ds_read_b128 v[170:173], v0 offset:6144
	ds_read_b128 v[166:169], v0 offset:6656
	s_waitcnt lgkmcnt(12)
	v_mfma_f32_32x32x16_bf16 v[18:33], v[6:9], v[106:109], v[18:33]
	v_exp_f32_e32 v124, v124
	v_exp_f32_e32 v125, v125
	s_waitcnt lgkmcnt(10)
	v_mfma_f32_32x32x16_bf16 v[34:49], v[2:5], v[190:193], v[34:49]
	v_exp_f32_e32 v126, v126
	v_exp_f32_e32 v127, v127
	s_waitcnt lgkmcnt(8)
	v_mfma_f32_32x32x16_bf16 v[18:33], v[2:5], v[194:197], v[18:33]
	v_exp_f32_e32 v128, v128
	v_exp_f32_e32 v129, v129
	s_add_i32 s16, s13, 0x2000
	s_cmpk_lg_i32 s13, 0x4000
	s_cselect_b32 s47, s16, 0
	s_waitcnt vmcnt(3) lgkmcnt(0)
	s_barrier
	v_add_u32_e32 v0, s33, v252
.Lfsk2_263:
	v_add_u32_e32 v207, s21, v251
	ds_read_b64_tr_b16 v[198:199], v207 offset:24576
	ds_read_b64_tr_b16 v[200:201], v207 offset:25088
	s_waitcnt lgkmcnt(9)
	v_mfma_f32_32x32x16_bf16 v[98:113], v[86:89], v[162:165], v[208:223]
	v_add_f32_e32 v230, v130, v131
	v_cvt_pk_bf16_f32 v150, v130, v131
	v_add_f32_e32 v231, v132, v133
	v_cvt_pk_bf16_f32 v151, v132, v133
	v_add_f32_e32 v230, v134, v230
	v_add_f32_e32 v231, v135, v231
	ds_read_b64_tr_b16 v[194:195], v207 offset:28672
	ds_read_b64_tr_b16 v[196:197], v207 offset:29184
	s_waitcnt lgkmcnt(10)
	v_mfma_f32_32x32x16_bf16 v[82:97], v[82:85], v[162:165], v[208:223]
	v_add_f32_e32 v230, v136, v230
	v_cvt_pk_bf16_f32 v152, v134, v135
	v_add_f32_e32 v231, v137, v231
	v_cvt_pk_bf16_f32 v153, v136, v137
	v_add_f32_e32 v230, v138, v230
	v_add_f32_e32 v231, v139, v231
	ds_read_b64_tr_b16 v[190:191], v207 offset:25600
	ds_read_b64_tr_b16 v[192:193], v207 offset:26112
	s_waitcnt lgkmcnt(11)
	v_mfma_f32_32x32x16_bf16 v[98:113], v[186:189], v[158:161], v[98:113]
	v_add_f32_e32 v230, v140, v230
	v_cvt_pk_bf16_f32 v10, v138, v139
	v_add_f32_e32 v231, v141, v231
	v_cvt_pk_bf16_f32 v11, v140, v141
	v_add_f32_e32 v230, v142, v230
	v_add_f32_e32 v231, v143, v231
	ds_read_b64_tr_b16 v[138:139], v207 offset:29696
	ds_read_b64_tr_b16 v[140:141], v207 offset:30208
	s_waitcnt lgkmcnt(12)
	v_mfma_f32_32x32x16_bf16 v[82:97], v[182:185], v[158:161], v[82:97]
	v_add_f32_e32 v230, v144, v230
	v_cvt_pk_bf16_f32 v12, v142, v143
	v_add_f32_e32 v231, v145, v231
	v_cvt_pk_bf16_f32 v13, v144, v145
	v_add_f32_e32 v230, v114, v230
	v_add_f32_e32 v231, v115, v231
	ds_read_b64_tr_b16 v[134:135], v207 offset:26624
	ds_read_b64_tr_b16 v[136:137], v207 offset:27136
	s_waitcnt lgkmcnt(13)
	v_mfma_f32_32x32x16_bf16 v[98:113], v[178:181], v[154:157], v[98:113]
	v_add_f32_e32 v230, v116, v230
	v_cvt_pk_bf16_f32 v6, v114, v115
	v_add_f32_e32 v231, v117, v231
	v_cvt_pk_bf16_f32 v7, v116, v117
	v_add_f32_e32 v230, v118, v230
	v_add_f32_e32 v231, v119, v231
	ds_read_b64_tr_b16 v[130:131], v207 offset:30720
	ds_read_b64_tr_b16 v[132:133], v207 offset:31232
	s_waitcnt lgkmcnt(14)
	v_mfma_f32_32x32x16_bf16 v[82:97], v[174:177], v[154:157], v[82:97]
	v_add_f32_e32 v230, v120, v230
	v_cvt_pk_bf16_f32 v8, v118, v119
	v_add_f32_e32 v231, v121, v231
	v_cvt_pk_bf16_f32 v9, v120, v121
	v_add_f32_e32 v230, v122, v230
	v_add_f32_e32 v231, v123, v231
	ds_read_b64_tr_b16 v[118:119], v207 offset:27648
	ds_read_b64_tr_b16 v[120:121], v207 offset:28160
	s_waitcnt lgkmcnt(14)
	v_mfma_f32_32x32x16_bf16 v[98:113], v[170:173], v[146:149], v[98:113]
	v_add_f32_e32 v230, v124, v230
	v_cvt_pk_bf16_f32 v2, v122, v123
	v_add_f32_e32 v231, v125, v231
	v_cvt_pk_bf16_f32 v3, v124, v125
	v_add_f32_e32 v230, v126, v230
	v_add_f32_e32 v231, v127, v231
	ds_read_b64_tr_b16 v[114:115], v207 offset:31744
	ds_read_b64_tr_b16 v[116:117], v207 offset:32256
	v_mfma_f32_32x32x16_bf16 v[82:97], v[166:169], v[146:149], v[82:97]
	v_add_f32_e32 v230, v128, v230
	v_cvt_pk_bf16_f32 v4, v126, v127
	v_add_f32_e32 v231, v129, v231
	v_cvt_pk_bf16_f32 v5, v128, v129
	s_add_u32 s56, s54, 0xa000
	s_addc_u32 s57, s55, 0
	s_add_i32 s16, s13, s43
	s_mov_b32 m0, s16
	s_nop 0
	global_load_lds_dwordx4 v202, s[56:57]
	s_add_u32 s56, s50, s14
	s_addc_u32 s57, s51, s15
	s_add_u32 s56, s56, 0x6000
	s_addc_u32 s57, s57, 0
	s_add_i32 s16, s47, s44
	s_mov_b32 m0, s16
	s_nop 0
	global_load_lds_dwordx4 v203, s[56:57]
	s_add_u32 s58, s52, s14
	s_addc_u32 s59, s53, s15
	s_add_u32 s58, s58, 0x6000
	s_addc_u32 s59, s59, 0
	s_add_i32 s16, s47, s45
	s_mov_b32 m0, s16
	s_nop 0
	global_load_lds_dwordx4 v203, s[58:59]
	v_add_f32_e32 v230, v230, v231
	v_add_f32_e32 v232, v206, v230
;   #define WB(a,b) do{ if constexpr(DV2){WAIT_BAR(b);} else {WAIT_BAR(a);} }while(0)
;   #define RESC() do{ if(resc){ asm volatile("s_waitcnt lgkmcnt(0)":::"memory"); \
;       _Pragma("unroll") for(int d_=0;d_<ND;++d_) _Pragma("unroll") for(int r=0;r<16;++r)o[d_][r]*=wsf[crow(r,hi)]; } }while(0)
;   #define ROT() do{sl_prev=sl_cur;sl_cur=sl_next;sl_next=(sl_next==(NSLOT-1)*SLOTB)?0:sl_next+SLOTB;}while(0)
;     ...
;   for(;t+5<NT;t+=2){
;     STEP(pB0,pB1,pA0,pA1,t,true,true,true);     WB(2,3); RESC(); ROT();
;     STEP(pA0,pA1,pB0,pB1,t+1,true,true,true);   WB(2,3); RESC(); ROT();
;   }
.Lfsk2_264:
	v_add_u32_e32 v14, s21, v249
	v_add_u32_e32 v15, 0xe800, v14
	s_waitcnt lgkmcnt(14)
	v_mfma_f32_32x32x16_bf16 v[66:81], v[150:153], v[198:201], v[66:81]
	v_exp_f32_e32 v98, v98
	v_exp_f32_e32 v99, v99
	ds_read_b64_tr_b16 v[122:123], v14 offset:59392
	ds_read_b64_tr_b16 v[124:125], v14 offset:59904
	s_waitcnt lgkmcnt(14)
	v_mfma_f32_32x32x16_bf16 v[50:65], v[150:153], v[194:197], v[50:65]
	v_exp_f32_e32 v100, v100
	v_exp_f32_e32 v101, v101
	ds_read_b64_tr_b16 v[126:127], v14 offset:63488
	ds_read_b64_tr_b16 v[128:129], v14 offset:64000
	s_waitcnt lgkmcnt(14)
	v_mfma_f32_32x32x16_bf16 v[66:81], v[10:13], v[190:193], v[66:81]
	v_exp_f32_e32 v102, v102
	v_exp_f32_e32 v103, v103
	ds_read_b64_tr_b16 v[142:143], v14 offset:60416
	ds_read_b64_tr_b16 v[144:145], v14 offset:60928
	s_waitcnt lgkmcnt(14)
	v_mfma_f32_32x32x16_bf16 v[50:65], v[10:13], v[138:141], v[50:65]
	v_exp_f32_e32 v104, v104
	v_exp_f32_e32 v105, v105
	ds_read_b64_tr_b16 v[138:139], v14 offset:64512
	ds_read_b64_tr_b16 v[140:141], v14 offset:65024
	s_waitcnt lgkmcnt(14)
	v_mfma_f32_32x32x16_bf16 v[66:81], v[6:9], v[134:137], v[66:81]
	v_exp_f32_e32 v106, v106
	v_exp_f32_e32 v107, v107
	ds_read_b64_tr_b16 v[134:135], v14 offset:61440
	ds_read_b64_tr_b16 v[136:137], v14 offset:61952
	s_waitcnt lgkmcnt(14)
	v_mfma_f32_32x32x16_bf16 v[50:65], v[6:9], v[130:133], v[50:65]
	v_exp_f32_e32 v108, v108
	v_exp_f32_e32 v109, v109
	ds_read_b64_tr_b16 v[130:131], v15 offset:6144
	ds_read_b64_tr_b16 v[132:133], v15 offset:6656
	s_waitcnt lgkmcnt(14)
	v_mfma_f32_32x32x16_bf16 v[66:81], v[2:5], v[118:121], v[66:81]
	v_exp_f32_e32 v110, v110
	v_exp_f32_e32 v111, v111
	ds_read_b64_tr_b16 v[118:119], v14 offset:62464
	ds_read_b64_tr_b16 v[120:121], v14 offset:62976
	s_waitcnt lgkmcnt(14)
	v_mfma_f32_32x32x16_bf16 v[50:65], v[2:5], v[114:117], v[50:65]
	v_exp_f32_e32 v112, v112
	v_exp_f32_e32 v113, v113
	ds_read_b64_tr_b16 v[114:115], v15 offset:7168
	ds_read_b64_tr_b16 v[116:117], v15 offset:7680
	s_waitcnt lgkmcnt(14)
	v_mfma_f32_32x32x16_bf16 v[34:49], v[150:153], v[122:125], v[34:49]
	v_exp_f32_e32 v82, v82
	v_exp_f32_e32 v83, v83
	s_waitcnt lgkmcnt(12)
	v_mfma_f32_32x32x16_bf16 v[18:33], v[150:153], v[126:129], v[18:33]
	v_exp_f32_e32 v84, v84
	v_exp_f32_e32 v85, v85
	v_add_u32_e32 v14, s47, v250
	ds_read_b128 v[194:197], v14
	ds_read_b128 v[186:189], v14 offset:512
	s_waitcnt lgkmcnt(12)
	v_mfma_f32_32x32x16_bf16 v[34:49], v[10:13], v[142:145], v[34:49]
	v_exp_f32_e32 v86, v86
	v_exp_f32_e32 v87, v87
	ds_read_b128 v[190:193], v14 offset:2048
	ds_read_b128 v[182:185], v14 offset:2560
	s_waitcnt lgkmcnt(12)
	v_mfma_f32_32x32x16_bf16 v[18:33], v[10:13], v[138:141], v[18:33]
	v_exp_f32_e32 v88, v88
	v_exp_f32_e32 v89, v89
	ds_read_b128 v[178:181], v14 offset:4096
	ds_read_b128 v[174:177], v14 offset:4608
	s_waitcnt lgkmcnt(12)
	v_mfma_f32_32x32x16_bf16 v[34:49], v[6:9], v[134:137], v[34:49]
	v_exp_f32_e32 v90, v90
	v_exp_f32_e32 v91, v91
	ds_read_b128 v[170:173], v14 offset:6144
	ds_read_b128 v[166:169], v14 offset:6656
	s_waitcnt lgkmcnt(12)
	v_mfma_f32_32x32x16_bf16 v[18:33], v[6:9], v[130:133], v[18:33]
	v_exp_f32_e32 v92, v92
	v_exp_f32_e32 v93, v93
	s_waitcnt lgkmcnt(10)
	v_mfma_f32_32x32x16_bf16 v[34:49], v[2:5], v[118:121], v[34:49]
	v_exp_f32_e32 v94, v94
	v_exp_f32_e32 v95, v95
	s_waitcnt lgkmcnt(8)
	v_mfma_f32_32x32x16_bf16 v[18:33], v[2:5], v[114:117], v[18:33]
	v_exp_f32_e32 v96, v96
	v_exp_f32_e32 v97, v97
	s_add_i32 s16, s47, 0x2000
	s_cmpk_lg_i32 s47, 0x4000
	s_cselect_b32 s46, s16, 0
	s_add_i32 s16, s20, 2
	s_add_u32 s14, s14, 0x4000
	s_addc_u32 s15, s15, 0
	s_cmp_ge_u32 s16, s39
	s_cbranch_scc1 .Lfsk2_xbar
	s_mov_b32 s20, s16
	s_mov_b32 s22, s13
	s_mov_b32 s21, s47
	s_mov_b32 s13, s46
	s_branch .Lfsk2_head
.Lfsk2_xbar:
	s_waitcnt vmcnt(3) lgkmcnt(0)
	s_barrier
	s_branch .LBB0_281

;   #define WB(a,b) do{ if constexpr(DV2){WAIT_BAR(b);} else {WAIT_BAR(a);} }while(0)
;   #define RESC() do{ if(resc){ asm volatile("s_waitcnt lgkmcnt(0)":::"memory"); \
;       _Pragma("unroll") for(int d_=0;d_<ND;++d_) _Pragma("unroll") for(int r=0;r<16;++r)o[d_][r]*=wsf[crow(r,hi)]; } }while(0)
;   #define ROT() do{sl_prev=sl_cur;sl_cur=sl_next;sl_next=(sl_next==(NSLOT-1)*SLOTB)?0:sl_next+SLOTB;}while(0)
;     ...
;   for(;t+5<NT;t+=2){
;     STEP(pB0,pB1,pA0,pA1,t,true,true,true);     WB(2,3); RESC(); ROT();
;     STEP(pA0,pA1,pB0,pB1,t+1,true,true,true);   WB(2,3); RESC(); ROT();
;   }
.Lattn0_steady_exit:
	v_lshl_add_u64 v[190:191], s[34:35], 0, v[208:209]
	v_lshl_add_u64 v[188:189], s[36:37], 0, v[210:211]
	s_branch .LBB0_861
.Lfsk0_head:
	s_waitcnt vmcnt(2) lgkmcnt(0)
	s_barrier
.Lfsk0_840:
	v_add_u32_e32 v192, s8, v204
	ds_read_b64_tr_b16 v[182:183], v192 offset:24576
	ds_read_b64_tr_b16 v[184:185], v192 offset:25088
	s_waitcnt lgkmcnt(9)
	v_mfma_f32_32x32x16_bf16 v[114:129], v[178:181], v[146:149], v[50:65]
	v_add_f32_e32 v212, v82, v83
	v_cvt_pk_bf16_f32 v134, v82, v83
	v_add_f32_e32 v213, v84, v85
	v_cvt_pk_bf16_f32 v135, v84, v85
	v_add_f32_e32 v212, v86, v212
	v_add_f32_e32 v213, v87, v213
	ds_read_b64_tr_b16 v[178:179], v192 offset:28672
	ds_read_b64_tr_b16 v[180:181], v192 offset:29184
	s_waitcnt lgkmcnt(10)
	v_mfma_f32_32x32x16_bf16 v[98:113], v[174:177], v[146:149], v[50:65]
	v_add_f32_e32 v212, v88, v212
	v_cvt_pk_bf16_f32 v136, v86, v87
	v_add_f32_e32 v213, v89, v213
	v_cvt_pk_bf16_f32 v137, v88, v89
	v_add_f32_e32 v212, v90, v212
	v_add_f32_e32 v213, v91, v213
	ds_read_b64_tr_b16 v[82:83], v192 offset:25600
	ds_read_b64_tr_b16 v[84:85], v192 offset:26112
	s_waitcnt lgkmcnt(11)
	v_mfma_f32_32x32x16_bf16 v[114:129], v[170:173], v[142:145], v[114:129]
	v_add_f32_e32 v212, v92, v212
	v_cvt_pk_bf16_f32 v10, v90, v91
	v_add_f32_e32 v213, v93, v213
	v_cvt_pk_bf16_f32 v11, v92, v93
	v_add_f32_e32 v212, v94, v212
	v_add_f32_e32 v213, v95, v213
	ds_read_b64_tr_b16 v[86:87], v192 offset:29696
	ds_read_b64_tr_b16 v[88:89], v192 offset:30208
	s_waitcnt lgkmcnt(12)
	v_mfma_f32_32x32x16_bf16 v[98:113], v[166:169], v[142:145], v[98:113]
	v_add_f32_e32 v212, v96, v212
	v_cvt_pk_bf16_f32 v12, v94, v95
	v_add_f32_e32 v213, v97, v213
	v_cvt_pk_bf16_f32 v13, v96, v97
	v_add_f32_e32 v212, v66, v212
	v_add_f32_e32 v213, v67, v213
	ds_read_b64_tr_b16 v[90:91], v192 offset:26624
	ds_read_b64_tr_b16 v[92:93], v192 offset:27136
	s_waitcnt lgkmcnt(13)
	v_mfma_f32_32x32x16_bf16 v[114:129], v[162:165], v[138:141], v[114:129]
	v_add_f32_e32 v212, v68, v212
	v_cvt_pk_bf16_f32 v6, v66, v67
	v_add_f32_e32 v213, v69, v213
	v_cvt_pk_bf16_f32 v7, v68, v69
	v_add_f32_e32 v212, v70, v212
	v_add_f32_e32 v213, v71, v213
	ds_read_b64_tr_b16 v[66:67], v192 offset:30720
	ds_read_b64_tr_b16 v[68:69], v192 offset:31232
	s_waitcnt lgkmcnt(14)
	v_mfma_f32_32x32x16_bf16 v[98:113], v[158:161], v[138:141], v[98:113]
	v_add_f32_e32 v212, v72, v212
	v_cvt_pk_bf16_f32 v8, v70, v71
	v_add_f32_e32 v213, v73, v213
	v_cvt_pk_bf16_f32 v9, v72, v73
	v_add_f32_e32 v212, v74, v212
	v_add_f32_e32 v213, v75, v213
	ds_read_b64_tr_b16 v[70:71], v192 offset:27648
	ds_read_b64_tr_b16 v[72:73], v192 offset:28160
	s_waitcnt lgkmcnt(14)
	v_mfma_f32_32x32x16_bf16 v[114:129], v[154:157], v[130:133], v[114:129]
	v_add_f32_e32 v212, v76, v212
	v_cvt_pk_bf16_f32 v2, v74, v75
	v_add_f32_e32 v213, v77, v213
	v_cvt_pk_bf16_f32 v3, v76, v77
	v_add_f32_e32 v212, v78, v212
	v_add_f32_e32 v213, v79, v213
	ds_read_b64_tr_b16 v[74:75], v192 offset:31744
	ds_read_b64_tr_b16 v[76:77], v192 offset:32256
	v_mfma_f32_32x32x16_bf16 v[98:113], v[150:153], v[130:133], v[98:113]
	v_add_f32_e32 v212, v80, v212
	v_cvt_pk_bf16_f32 v4, v78, v79
	v_add_f32_e32 v213, v81, v213
	v_cvt_pk_bf16_f32 v5, v80, v81
	s_add_u32 s38, s34, s52
	s_addc_u32 s39, s35, s53
	s_add_i32 s8, s16, s26
	s_mov_b32 m0, s8
	s_nop 0
	global_load_lds_dwordx4 v208, s[38:39]
	s_add_u32 s40, s36, s52
	s_addc_u32 s41, s37, s53
	s_add_i32 s8, s14, s27
	s_mov_b32 m0, s8
	s_nop 0
	global_load_lds_dwordx4 v210, s[40:41]
	v_add_f32_e32 v212, v212, v213
	v_add_f32_e32 v192, v206, v212
.Lfsk0_841:
	s_waitcnt lgkmcnt(14)
	v_mfma_f32_32x32x16_bf16 v[34:49], v[134:137], v[182:185], v[34:49]
	v_exp_f32_e32 v114, v114
	v_exp_f32_e32 v115, v115
	v_exp_f32_e32 v116, v116
	v_exp_f32_e32 v117, v117
	s_waitcnt lgkmcnt(12)
	v_mfma_f32_32x32x16_bf16 v[18:33], v[134:137], v[178:181], v[18:33]
	v_exp_f32_e32 v118, v118
	v_exp_f32_e32 v119, v119
	v_exp_f32_e32 v120, v120
	v_exp_f32_e32 v121, v121
	v_add_u32_e32 v94, s14, v203
	ds_read_b128 v[78:81], v94
	ds_read_b128 v[178:181], v94 offset:512
	s_waitcnt lgkmcnt(12)
	v_mfma_f32_32x32x16_bf16 v[34:49], v[10:13], v[82:85], v[34:49]
	v_exp_f32_e32 v122, v122
	v_exp_f32_e32 v123, v123
	v_exp_f32_e32 v124, v124
	v_exp_f32_e32 v125, v125
	ds_read_b128 v[182:185], v94 offset:2048
	ds_read_b128 v[174:177], v94 offset:2560
	s_waitcnt lgkmcnt(12)
	v_mfma_f32_32x32x16_bf16 v[18:33], v[10:13], v[86:89], v[18:33]
	v_exp_f32_e32 v126, v126
	v_exp_f32_e32 v127, v127
	v_exp_f32_e32 v128, v128
	v_exp_f32_e32 v129, v129
	ds_read_b128 v[170:173], v94 offset:4096
	ds_read_b128 v[166:169], v94 offset:4608
	s_waitcnt lgkmcnt(12)
	v_mfma_f32_32x32x16_bf16 v[34:49], v[6:9], v[90:93], v[34:49]
	v_exp_f32_e32 v98, v98
	v_exp_f32_e32 v99, v99
	v_exp_f32_e32 v100, v100
	v_exp_f32_e32 v101, v101
	ds_read_b128 v[162:165], v94 offset:6144
	ds_read_b128 v[158:161], v94 offset:6656
	s_waitcnt lgkmcnt(12)
	v_mfma_f32_32x32x16_bf16 v[18:33], v[6:9], v[66:69], v[18:33]
	v_exp_f32_e32 v102, v102
	v_exp_f32_e32 v103, v103
	v_exp_f32_e32 v104, v104
	v_exp_f32_e32 v105, v105
	s_waitcnt lgkmcnt(10)
	v_mfma_f32_32x32x16_bf16 v[34:49], v[2:5], v[70:73], v[34:49]
	v_exp_f32_e32 v106, v106
	v_exp_f32_e32 v107, v107
	v_exp_f32_e32 v108, v108
	v_exp_f32_e32 v109, v109
	s_waitcnt lgkmcnt(8)
	v_mfma_f32_32x32x16_bf16 v[18:33], v[2:5], v[74:77], v[18:33]
	v_exp_f32_e32 v110, v110
	v_exp_f32_e32 v111, v111
	v_exp_f32_e32 v112, v112
	v_exp_f32_e32 v113, v113
	s_add_i32 s8, s14, 0x2000
	s_cmpk_lg_i32 s14, 0x4000
	s_cselect_b32 s28, s8, 0
	s_waitcnt vmcnt(2) lgkmcnt(0)
	s_barrier
;   #define WB(a,b) do{ if constexpr(DV2){WAIT_BAR(b);} else {WAIT_BAR(a);} }while(0)
;   #define RESC() do{ if(resc){ asm volatile("s_waitcnt lgkmcnt(0)":::"memory"); \
;       _Pragma("unroll") for(int d_=0;d_<ND;++d_) _Pragma("unroll") for(int r=0;r<16;++r)o[d_][r]*=wsf[crow(r,hi)]; } }while(0)
;   #define ROT() do{sl_prev=sl_cur;sl_cur=sl_next;sl_next=(sl_next==(NSLOT-1)*SLOTB)?0:sl_next+SLOTB;}while(0)
;     ...
;   for(;t+5<NT;t+=2){
;     STEP(pB0,pB1,pA0,pA1,t,true,true,true);     WB(2,3); RESC(); ROT();
;     STEP(pA0,pA1,pB0,pB1,t+1,true,true,true);   WB(2,3); RESC(); ROT();
;   }
.Lfsk0_843:
	v_add_u32_e32 v194, s16, v204
	ds_read_b64_tr_b16 v[154:155], v194 offset:24576
	ds_read_b64_tr_b16 v[156:157], v194 offset:25088
	s_waitcnt lgkmcnt(9)
	v_mfma_f32_32x32x16_bf16 v[82:97], v[78:81], v[146:149], v[50:65]
	v_add_f32_e32 v212, v114, v115
	v_cvt_pk_bf16_f32 v134, v114, v115
	v_add_f32_e32 v213, v116, v117
	v_cvt_pk_bf16_f32 v135, v116, v117
	v_add_f32_e32 v212, v118, v212
	v_add_f32_e32 v213, v119, v213
	ds_read_b64_tr_b16 v[150:151], v194 offset:28672
	ds_read_b64_tr_b16 v[152:153], v194 offset:29184
	s_waitcnt lgkmcnt(10)
	v_mfma_f32_32x32x16_bf16 v[66:81], v[178:181], v[146:149], v[50:65]
	v_add_f32_e32 v212, v120, v212
	v_cvt_pk_bf16_f32 v136, v118, v119
	v_add_f32_e32 v213, v121, v213
	v_cvt_pk_bf16_f32 v137, v120, v121
	v_add_f32_e32 v212, v122, v212
	v_add_f32_e32 v213, v123, v213
	ds_read_b64_tr_b16 v[114:115], v194 offset:25600
	ds_read_b64_tr_b16 v[116:117], v194 offset:26112
	s_waitcnt lgkmcnt(11)
	v_mfma_f32_32x32x16_bf16 v[82:97], v[182:185], v[142:145], v[82:97]
	v_add_f32_e32 v212, v124, v212
	v_cvt_pk_bf16_f32 v10, v122, v123
	v_add_f32_e32 v213, v125, v213
	v_cvt_pk_bf16_f32 v11, v124, v125
	v_add_f32_e32 v212, v126, v212
	v_add_f32_e32 v213, v127, v213
	ds_read_b64_tr_b16 v[118:119], v194 offset:29696
	ds_read_b64_tr_b16 v[120:121], v194 offset:30208
	s_waitcnt lgkmcnt(12)
	v_mfma_f32_32x32x16_bf16 v[66:81], v[174:177], v[142:145], v[66:81]
	v_add_f32_e32 v212, v128, v212
	v_cvt_pk_bf16_f32 v12, v126, v127
	v_add_f32_e32 v213, v129, v213
	v_cvt_pk_bf16_f32 v13, v128, v129
	v_add_f32_e32 v212, v98, v212
	v_add_f32_e32 v213, v99, v213
	ds_read_b64_tr_b16 v[122:123], v194 offset:26624
	ds_read_b64_tr_b16 v[124:125], v194 offset:27136
	s_waitcnt lgkmcnt(13)
	v_mfma_f32_32x32x16_bf16 v[82:97], v[170:173], v[138:141], v[82:97]
	v_add_f32_e32 v212, v100, v212
	v_cvt_pk_bf16_f32 v6, v98, v99
	v_add_f32_e32 v213, v101, v213
	v_cvt_pk_bf16_f32 v7, v100, v101
	v_add_f32_e32 v212, v102, v212
	v_add_f32_e32 v213, v103, v213
	ds_read_b64_tr_b16 v[98:99], v194 offset:30720
	ds_read_b64_tr_b16 v[100:101], v194 offset:31232
	s_waitcnt lgkmcnt(14)
	v_mfma_f32_32x32x16_bf16 v[66:81], v[166:169], v[138:141], v[66:81]
	v_add_f32_e32 v212, v104, v212
	v_cvt_pk_bf16_f32 v8, v102, v103
	v_add_f32_e32 v213, v105, v213
	v_cvt_pk_bf16_f32 v9, v104, v105
	v_add_f32_e32 v212, v106, v212
	v_add_f32_e32 v213, v107, v213
	ds_read_b64_tr_b16 v[102:103], v194 offset:27648
	ds_read_b64_tr_b16 v[104:105], v194 offset:28160
	s_waitcnt lgkmcnt(14)
	v_mfma_f32_32x32x16_bf16 v[82:97], v[162:165], v[130:133], v[82:97]
	v_add_f32_e32 v212, v108, v212
	v_cvt_pk_bf16_f32 v2, v106, v107
	v_add_f32_e32 v213, v109, v213
	v_cvt_pk_bf16_f32 v3, v108, v109
	v_add_f32_e32 v212, v110, v212
	v_add_f32_e32 v213, v111, v213
	ds_read_b64_tr_b16 v[106:107], v194 offset:31744
	ds_read_b64_tr_b16 v[108:109], v194 offset:32256
	v_mfma_f32_32x32x16_bf16 v[66:81], v[158:161], v[130:133], v[66:81]
	v_add_f32_e32 v212, v112, v212
	v_cvt_pk_bf16_f32 v4, v110, v111
	v_add_f32_e32 v213, v113, v213
	v_cvt_pk_bf16_f32 v5, v112, v113
	s_add_i32 s8, s14, s26
	s_mov_b32 m0, s8
	s_nop 0
	global_load_lds_dwordx4 v208, s[34:35]
	s_add_i32 s8, s28, s27
	s_mov_b32 m0, s8
	s_nop 0
	global_load_lds_dwordx4 v210, s[36:37]
	v_add_f32_e32 v212, v212, v213
	v_add_f32_e32 v206, v192, v212
.Lfsk0_844:
	s_waitcnt lgkmcnt(14)
	v_mfma_f32_32x32x16_bf16 v[34:49], v[134:137], v[154:157], v[34:49]
	v_exp_f32_e32 v82, v82
	v_exp_f32_e32 v83, v83
	v_exp_f32_e32 v84, v84
	v_exp_f32_e32 v85, v85
	s_waitcnt lgkmcnt(12)
	v_mfma_f32_32x32x16_bf16 v[18:33], v[134:137], v[150:153], v[18:33]
	v_exp_f32_e32 v86, v86
	v_exp_f32_e32 v87, v87
	v_exp_f32_e32 v88, v88
	v_exp_f32_e32 v89, v89
	v_add_u32_e32 v110, s28, v203
	ds_read_b128 v[178:181], v110
	ds_read_b128 v[174:177], v110 offset:512
	s_waitcnt lgkmcnt(12)
	v_mfma_f32_32x32x16_bf16 v[34:49], v[10:13], v[114:117], v[34:49]
	v_exp_f32_e32 v90, v90
	v_exp_f32_e32 v91, v91
	v_exp_f32_e32 v92, v92
	v_exp_f32_e32 v93, v93
	ds_read_b128 v[170:173], v110 offset:2048
	ds_read_b128 v[166:169], v110 offset:2560
	s_waitcnt lgkmcnt(12)
	v_mfma_f32_32x32x16_bf16 v[18:33], v[10:13], v[118:121], v[18:33]
	v_exp_f32_e32 v94, v94
	v_exp_f32_e32 v95, v95
	v_exp_f32_e32 v96, v96
	v_exp_f32_e32 v97, v97
	ds_read_b128 v[162:165], v110 offset:4096
	ds_read_b128 v[158:161], v110 offset:4608
	s_waitcnt lgkmcnt(12)
	v_mfma_f32_32x32x16_bf16 v[34:49], v[6:9], v[122:125], v[34:49]
	v_exp_f32_e32 v66, v66
	v_exp_f32_e32 v67, v67
	v_exp_f32_e32 v68, v68
	v_exp_f32_e32 v69, v69
	ds_read_b128 v[154:157], v110 offset:6144
	ds_read_b128 v[150:153], v110 offset:6656
	s_waitcnt lgkmcnt(12)
	v_mfma_f32_32x32x16_bf16 v[18:33], v[6:9], v[98:101], v[18:33]
	v_exp_f32_e32 v70, v70
	v_exp_f32_e32 v71, v71
	v_exp_f32_e32 v72, v72
	v_exp_f32_e32 v73, v73
	s_waitcnt lgkmcnt(10)
	v_mfma_f32_32x32x16_bf16 v[34:49], v[2:5], v[102:105], v[34:49]
	v_exp_f32_e32 v74, v74
	v_exp_f32_e32 v75, v75
	v_exp_f32_e32 v76, v76
	v_exp_f32_e32 v77, v77
	s_waitcnt lgkmcnt(8)
	v_mfma_f32_32x32x16_bf16 v[18:33], v[2:5], v[106:109], v[18:33]
	v_exp_f32_e32 v78, v78
	v_exp_f32_e32 v79, v79
	v_exp_f32_e32 v80, v80
	v_exp_f32_e32 v81, v81
	s_add_i32 s8, s28, 0x2000
	s_cmpk_lg_i32 s28, 0x4000
	s_cselect_b32 s29, s8, 0
	s_add_i32 s8, s15, 2
	s_add_u32 s36, s36, 0x4000
	s_addc_u32 s37, s37, 0
	s_add_u32 s34, s34, 0x4000
	s_addc_u32 s35, s35, 0
	s_cmp_ge_u32 s8, s25
	s_cbranch_scc1 .Lfsk0_xbar
	s_mov_b32 s15, s8
	s_mov_b32 s8, s14
	s_mov_b32 s16, s28
	s_mov_b32 s14, s29
	s_branch .Lfsk0_head
.Lfsk0_xbar:
	s_waitcnt vmcnt(2) lgkmcnt(0)
	s_barrier
	s_branch .Lattn0_steady_exit
